# P1 unit order rotated per XCC group (offset 20 units = 2.5 weight-tile columns) so XCCs do not fetch the same B tiles at once
# speedup vs baseline: 1.0077x; 1.0013x over previous
; template <class Epi, class Sched, bool ALIGN_EPI = false, bool SP2 = false>
; __device__ __forceinline__ void gemm_phase(PG8_LAS unsigned char* lds, const Gemm g, const Sched& S, const Epi& E) {
;     const int tid = threadIdx.x, wid = __builtin_amdgcn_readfirstlane(tid >> 6), lane = tid & 63, wr = wid >> 2, wc = wid & 3, fr = lane & 15, fq = lane >> 4;
;     const int K = g.K, nt = K / BK;
;     unsigned voffA[2], voffB[2];
; #pragma unroll
;     for (int i = 0; i < 2; ++i) { int R, C; stage_rc(tid * 16 + i * 8192, R, C); const int Rb = Epi::PERM ? ((R & ~31) + perm32(R & 31)) : R;
;         voffA[i] = (unsigned)(R * K + C) * 2u; voffB[i] = (unsigned)(Rb * K + C) * 2u; }
;     const size_t kstep = (size_t)(BK * 2);
;     const size_t hstep = (size_t)HALF * K * 2;
;     const size_t tstep = 2 * hstep;
;     const unsigned ldsw = (unsigned)wid * 1024u;
;     const int aoff = lds_byte(wr * 64 + fr, fq * 8), boff = lds_byte(wc * 32 + fr, fq * 8);
;     ...
;     Unit cur, nxt; int ui = 0;
;     if (!S.next(0, cur)) return;
;     f32x4 acc[2][2][4][2];
; #pragma unroll
;     for (int a = 0; a < 2; ++a)
; #pragma unroll
;         for (int b = 0; b < 2; ++b)
; #pragma unroll
;             for (int m = 0; m < 4; ++m)
; #pragma unroll
;                 for (int n = 0; n < 2; ++n) acc[a][b][m][n] = (f32x4){0.f, 0.f, 0.f, 0.f};
;     bf16x8 At[4][2], B0[2][2], B1[2][2];
;     const char* cA = (const char*)g.A + (size_t)cur.pm * tstep; const char* cB = (const char*)g.Bt + (size_t)cur.pn * tstep;
;     S.a_ready(cur);
;     if constexpr (SP2) {
;         PG8_STAGE(PG8_SB(0, 0), cB, voffB); PG8_STAGE(PG8_SB(0, 1), cB + hstep, voffB); PG8_STAGE(PG8_SA(0, 0), cA, voffA); PG8_STAGE(PG8_SA(0, 1), cA + hstep, voffA);
;         if (wr == 1) PG8_BAR;
;         PG8_WAIT_V(2); PG8_BAR;
;         PG8_STAGE(PG8_SB(1, 0), cB + kstep, voffB); PG8_STAGE(PG8_SA(1, 0), cA + kstep, voffA); PG8_STAGE(PG8_SB(1, 1), cB + hstep + kstep, voffB);
;         PG8_WAIT_V(6); PG8_BAR;
;     } else {
;         PG8_STAGE(PG8_SB(0, 0), cB, voffB); PG8_STAGE(PG8_SA(0, 0), cA, voffA); PG8_STAGE(PG8_SB(0, 1), cB + hstep, voffB); PG8_STAGE(PG8_SA(0, 1), cA + hstep, voffA);
;         if (wr == 1) PG8_BAR;
;         PG8_WAIT_V(4); PG8_BAR;
;         PG8_STAGE(PG8_SB(1, 0), cB + kstep, voffB); PG8_STAGE(PG8_SA(1, 0), cA + kstep, voffA); PG8_STAGE(PG8_SB(1, 1), cB + hstep + kstep, voffB);
.LBB0_116:
	s_cmp_lt_i32 s82, 2
	s_cselect_b64 s[4:5], -1, 0
	s_and_b64 s[4:5], s[4:5], s[0:1]
	s_andn2_b64 vcc, exec, s[4:5]
	s_cbranch_vccnz .LBB0_141
	s_cmpk_gt_i32 s2, 0x4ff
	v_readfirstlane_b32 s1, v188
	s_cbranch_scc1 .LBB0_141
	v_lshrrev_b32_e32 v2, 1, v188
	v_lshrrev_b32_e32 v3, 5, v188
	v_and_b32_e32 v2, 24, v2
	v_and_b32_e32 v3, 4, v3
	v_bfe_u32 v4, v188, 2, 2
	s_add_u32 s46, s78, 0x2000000
	v_lshlrev_b32_e32 v0, 4, v188
	v_and_b32_e32 v1, 32, v188
	v_bfe_u32 v10, v188, 2, 4
	v_or3_b32 v2, v3, v4, v2
	v_lshrrev_b32_e32 v3, 3, v188
	s_movk_i32 s0, 0x70
	s_addc_u32 s47, s79, 0
	v_bitop3_b32 v8, v0, v1, 48 bitop3:0x6c
	v_and_b32_e32 v9, 64, v188
	v_and_or_b32 v4, v3, s0, v10
	s_movk_i32 s0, 0x60
	v_add_u32_e32 v11, 0x2000, v0
	s_add_u32 s48, s78, 0xc00000
	v_or_b32_e32 v1, v8, v9
	v_and_or_b32 v3, v3, s0, v2
	v_lshrrev_b32_e32 v0, 7, v11
	s_movk_i32 s0, 0xf0
	s_addc_u32 s49, s79, 0
	v_lshl_or_b32 v146, v3, 11, v1
	v_and_or_b32 v3, v0, s0, v10
	s_movk_i32 s0, 0xe0
	s_ashr_i32 s51, s2, 31
	v_and_or_b32 v0, v0, s0, v2
	s_lshr_b32 s0, s51, 29
	s_add_i32 s0, s2, s0
	s_lshr_b32 s16, s1, 6
	s_ashr_i32 s6, s0, 3
	s_and_b32 s0, s0, -8
	s_lshr_b32 s14, s1, 8
	s_lshl_b32 s50, s16, 10
	s_sub_i32 s0, s2, s0
	s_cmp_lt_i32 s0, 0
	s_movk_i32 s52, 0xa1
	s_cselect_b32 s7, s52, 0xa0
	s_mul_i32 s0, s0, s7
	s_add_i32 s0, s0, s6
	s_mul_hi_i32 s6, s0, 0x66666667
	s_lshr_b32 s7, s6, 31
	s_ashr_i32 s6, s6, 6
	s_add_i32 s6, s6, s7
	s_lshl_b32 s7, s6, 3
	s_mulk_i32 s6, 0xa0
	s_sub_i32 s6, s0, s6
	s_sext_i32_i16 s0, s6
	s_bfe_u32 s0, s0, 0x3001c
	s_add_i32 s8, s6, s0
	s_sext_i32_i16 s0, s8
	s_and_b32 s8, s8, 0xfff8
	s_sub_i32 s6, s6, s8
	s_sext_i32_i16 s6, s6
	s_lshr_b32 s0, s0, 3
	s_add_i32 s6, s7, s6
	s_lshr_b32 s7, s2, 3
	s_and_b32 s8, s2, 7
	s_mul_i32 s8, s8, 20
	s_add_i32 s7, s7, s8
	s_sub_i32 s8, s7, 0xa0
	s_cmp_ge_i32 s8, 0
	s_cselect_b32 s7, s8, s7
	s_lshr_b32 s0, s7, 3
	s_and_b32 s7, s7, 7
	s_and_b32 s8, s2, 7
	s_lshl_b32 s8, s8, 3
	s_add_i32 s6, s8, s7
	s_ashr_i32 s7, s6, 31
	s_bfe_i64 s[10:11], s[0:1], 0x100000
	s_lshl_b64 s[8:9], s[6:7], 19
	s_lshl_b64 s[10:11], s[10:11], 19
	s_add_u32 s42, s48, s10
	s_addc_u32 s43, s49, s11
	s_add_i32 s53, s50, 0
	s_add_i32 m0, s53, 0x10000
	v_lshl_or_b32 v150, v0, 11, v1
	global_load_lds_dwordx4 v146, s[42:43]
	s_add_i32 m0, s53, 0x12000
	s_add_u32 s10, s42, 0x40000
	global_load_lds_dwordx4 v150, s[42:43]
	s_addc_u32 s11, s43, 0
	s_add_i32 m0, s53, 0x14000
	v_lshl_or_b32 v144, v4, 11, v1
	global_load_lds_dwordx4 v146, s[10:11]
	s_add_i32 m0, s53, 0x16000
	s_add_u32 s40, s46, s8
	s_addc_u32 s41, s47, s9
	s_waitcnt lgkmcnt(0)
	s_add_i32 s58, s53, 0x2000
	global_load_lds_dwordx4 v150, s[10:11]
	s_mov_b32 m0, s53
	s_add_u32 s8, s40, 0x40000
	v_lshl_or_b32 v148, v3, 11, v1
	global_load_lds_dwordx4 v144, s[40:41]
	s_mov_b32 m0, s58
	s_addc_u32 s9, s41, 0
	s_add_i32 s59, s53, 0x4000
	global_load_lds_dwordx4 v148, s[40:41]
	s_mov_b32 m0, s59
	s_add_i32 s60, s53, 0x6000
	global_load_lds_dwordx4 v144, s[8:9]
	s_mov_b32 m0, s60
	v_mov_b32_e32 v153, 0
	global_load_lds_dwordx4 v148, s[8:9]
	v_mov_b32_e32 v147, v153
	v_mov_b32_e32 v151, v153
	v_mov_b32_e32 v145, v153
	v_mov_b32_e32 v149, v153
	s_cmp_eq_u32 s14, 1
	s_mov_b32 s7, 0
	v_lshl_add_u64 v[6:7], s[42:43], 0, v[146:147]
	v_lshl_add_u64 v[4:5], s[42:43], 0, v[150:151]
	v_lshl_add_u64 v[0:1], s[40:41], 0, v[144:145]
	s_cselect_b64 s[8:9], -1, 0
	s_cmp_lg_u32 s14, 1
	v_lshl_add_u64 v[2:3], s[40:41], 0, v[148:149]
	s_cbranch_scc1 .LBB0_120
	s_barrier

;     __device__ __forceinline__ bool next(int i, Unit& u) const { const unsigned c = (i < 4) ? ((list >> (8 * i)) & 0xffu) : 0xffu; if (c == 0xffu) return false; u.pm = pm0 + (int)(c & 7u); u.pn = (int)(c >> 3); return true; }
;     __device__ __forceinline__ bool next(int i, Unit& u) const { if (!base.next(i, u)) return false; u.pm = (u.pm / 6) * 8 + (u.pm % 6); return true; }
;     __host__ __device__ bool next(int i, Unit& u) const {
;         const long L = (long)i * G + c; if (L >= nwg) return false;
;         int wgid = (int)L; { const int q = nwg / NXCD, r = nwg % NXCD, xcd = wgid % NXCD, off = wgid / NXCD; wgid = (xcd < r ? xcd * (q + 1) : r * (q + 1) + (xcd - r) * q) + off; }
;         const int nig = WGM * nN, gid = wgid / nig, fm = gid * WGM, gsz = (nM - fm) < WGM ? (nM - fm) : WGM;
;         u.pm = fm + ((wgid % nig) % gsz); u.pn = (wgid % nig) / gsz; return true;
;     }
; template <class Epi, class Sched, bool ALIGN_EPI = false, bool SP2 = false>
; __device__ __forceinline__ void gemm_phase(PG8_LAS unsigned char* lds, const Gemm g, const Sched& S, const Epi& E) {
;     ...
;         const bool has_next = S.next(ui + 1, nxt);
;         const char* nA = has_next ? (const char*)g.A + (size_t)nxt.pm * tstep : cA; const char* nB = has_next ? (const char*)g.Bt + (size_t)nxt.pn * tstep : cB;
.LBB0_123:
	s_add_i32 s93, s93, 1
	s_mul_i32 s0, s93, s61
	s_mul_hi_u32 s1, s93, s68
	s_add_i32 s1, s1, s0
	s_mul_i32 s0, s93, s68
	s_add_u32 s36, s0, s2
	s_addc_u32 s37, s1, s51
	v_cmp_gt_i64_e32 vcc, s[36:37], v[166:167]
	v_cmp_lt_i64_e64 s[0:1], s[36:37], v[164:165]
	s_cbranch_vccnz .LBB0_125
	s_ashr_i32 s30, s36, 31
	s_lshr_b32 s30, s30, 29
	s_add_i32 s30, s36, s30
	s_ashr_i32 s31, s30, 3
	s_and_b32 s30, s30, -8
	s_sub_i32 s30, s36, s30
	s_cmp_lt_i32 s30, 0
	s_cselect_b32 s34, s52, 0xa0
	s_mul_i32 s30, s30, s34
	s_add_i32 s30, s30, s31
	s_mul_hi_i32 s31, s30, 0x66666667
	s_lshr_b32 s34, s31, 31
	s_ashr_i32 s31, s31, 6
	s_add_i32 s31, s31, s34
	s_lshl_b32 s34, s31, 3
	s_sub_i32 s35, 64, s34
	s_min_i32 s35, s35, 8
	s_abs_i32 s36, s35
	v_cvt_f32_u32_e32 v0, s36
	s_sub_i32 s38, 0, s36
	s_mulk_i32 s31, 0xa0
	s_sub_i32 s31, s30, s31
	v_rcp_iflag_f32_e32 v0, v0
	s_abs_i32 s30, s31
	s_xor_b32 s37, s31, s35
	s_ashr_i32 s37, s37, 31
	v_mul_f32_e32 v0, 0x4f7ffffe, v0
	v_cvt_u32_f32_e32 v0, v0
	s_nop 0
	v_readfirstlane_b32 s39, v0
	s_mul_i32 s38, s38, s39
	s_mul_hi_u32 s38, s39, s38
	s_add_i32 s39, s39, s38
	s_mul_hi_u32 s38, s30, s39
	s_mul_i32 s39, s38, s36
	s_sub_i32 s30, s30, s39
	s_add_i32 s44, s38, 1
	s_sub_i32 s39, s30, s36
	s_cmp_ge_u32 s30, s36
	s_cselect_b32 s38, s44, s38
	s_cselect_b32 s30, s39, s30
	s_add_i32 s39, s38, 1
	s_cmp_ge_u32 s30, s36
	s_cselect_b32 s30, s39, s38
	s_xor_b32 s30, s30, s37
	s_sub_i32 s30, s30, s37
	s_mul_i32 s35, s30, s35
	s_sub_i32 s31, s31, s35
	s_add_i32 s34, s34, s31
	s_lshl_b32 s31, s93, 5
	s_lshr_b32 s35, s2, 3
	s_add_i32 s31, s31, s35
	s_and_b32 s35, s2, 7
	s_mul_i32 s35, s35, 20
	s_add_i32 s31, s31, s35
	s_sub_i32 s35, s31, 0xa0
	s_cmp_ge_i32 s35, 0
	s_cselect_b32 s31, s35, s31
	s_lshr_b32 s30, s31, 3
	s_and_b32 s31, s31, 7
	s_and_b32 s35, s2, 7
	s_lshl_b32 s35, s35, 3
	s_add_i32 s34, s35, s31
